# v11 + P0 loop restructured: next item's loads issued before the LDS transpose and stores of the current item (deeper prefetch)
# baseline (speedup 1.0000x reference)
.Lp0_dst_init:
	s_add_u32 s22, s8, s27
	s_addc_u32 s23, s9, 0
	s_waitcnt lgkmcnt(0)
	s_cmp_eq_u32 s13, 0
	s_cselect_b32 s16, s14, s16
	s_cselect_b32 s17, s15, s17
	s_mov_b32 s4, 0
	s_add_i32 s25, s4, 0
	s_min_i32 s25, s25, s5
	s_lshl_b32 s25, s25, 11
	s_add_u32 s25, s25, s10

.Lp0_segok_i0:
	s_sub_u32 s26, s25, s7
	s_mul_hi_u32 s27, s26, s20
	s_mul_i32 s28, s27, s19
	s_sub_u32 s28, s26, s28
	s_lshl_b32 s29, s28, 5
	s_lshl_b32 s30, s27, 6
	s_mul_i32 s31, s30, s18
	s_lshl_b32 s34, s29, 2
	s_add_u32 s31, s31, s34
	s_add_u32 s56, s14, s31
	s_addc_u32 s57, s15, 0
	s_add_u32 s58, s56, s18
	s_addc_u32 s59, s57, 0
	s_add_u32 s60, s58, s18
	s_addc_u32 s61, s59, 0
	s_add_u32 s62, s60, s18
	s_addc_u32 s63, s61, 0
	s_add_u32 s64, s62, s18
	s_addc_u32 s65, s63, 0
	s_add_u32 s66, s64, s18
	s_addc_u32 s67, s65, 0
	s_add_u32 s68, s66, s18
	s_addc_u32 s69, s67, 0
	s_add_u32 s70, s68, s18
	s_addc_u32 s71, s69, 0
	s_lshl_b32 s34, s30, 2
	s_add_u32 s72, s16, s34
	s_addc_u32 s73, s17, 0
	s_cmpk_ge_u32 s29, 0x1600
	s_cselect_b32 s34, 1, 0
	s_and_b32 s34, s34, s24
	s_mul_i32 s35, s34, 0x1600
	s_sub_u32 s35, s29, s35
	s_lshr_b32 s36, s35, 7
	s_lshl_b32 s36, s36, 8
	s_lshl_b32 s37, s34, 7
	s_add_u32 s36, s36, s37
	s_and_b32 s37, s35, 0x7f
	s_add_u32 s36, s36, s37
	s_cmp_eq_u32 s24, 0
	s_cselect_b32 s36, s29, s36
	s_lshr_b32 s37, s36, 8
	s_mul_i32 s37, s37, s21
	s_add_u32 s37, s37, s27
	s_lshl_b32 s37, s37, 8
	s_and_b32 s38, s36, 0xff
	s_add_u32 s37, s37, s38
	s_lshl_b32 s37, s37, 7
	s_add_u32 s46, s22, s37
	s_addc_u32 s47, s23, 0
	s_mov_b32 s48, s13
	v_mad_u32_u24 v10, v2, s18, v1
	global_load_dwordx4 v[28:31], v3, s[72:73]
	global_load_dwordx4 v[32:35], v3, s[72:73] offset:16
	global_load_dwordx4 v[36:39], v10, s[56:57] nt
	global_load_dwordx4 v[40:43], v10, s[58:59] nt
	global_load_dwordx4 v[44:47], v10, s[60:61] nt
	global_load_dwordx4 v[48:51], v10, s[62:63] nt
	global_load_dwordx4 v[52:55], v10, s[64:65] nt
	global_load_dwordx4 v[56:59], v10, s[66:67] nt
	global_load_dwordx4 v[60:63], v10, s[68:69] nt
	global_load_dwordx4 v[64:67], v10, s[70:71] nt
	s_add_i32 s25, s4, 1
	s_min_i32 s25, s25, s5
	s_lshl_b32 s25, s25, 11
	s_add_u32 s25, s25, s10

.Lp0_segok_i1:
	s_sub_u32 s26, s25, s7
	s_mul_hi_u32 s27, s26, s20
	s_mul_i32 s28, s27, s19
	s_sub_u32 s28, s26, s28
	s_lshl_b32 s29, s28, 5
	s_lshl_b32 s30, s27, 6
	s_mul_i32 s31, s30, s18
	s_lshl_b32 s34, s29, 2
	s_add_u32 s31, s31, s34
	s_add_u32 s56, s14, s31
	s_addc_u32 s57, s15, 0
	s_add_u32 s58, s56, s18
	s_addc_u32 s59, s57, 0
	s_add_u32 s60, s58, s18
	s_addc_u32 s61, s59, 0
	s_add_u32 s62, s60, s18
	s_addc_u32 s63, s61, 0
	s_add_u32 s64, s62, s18
	s_addc_u32 s65, s63, 0
	s_add_u32 s66, s64, s18
	s_addc_u32 s67, s65, 0
	s_add_u32 s68, s66, s18
	s_addc_u32 s69, s67, 0
	s_add_u32 s70, s68, s18
	s_addc_u32 s71, s69, 0
	s_lshl_b32 s34, s30, 2
	s_add_u32 s72, s16, s34
	s_addc_u32 s73, s17, 0
	s_cmpk_ge_u32 s29, 0x1600
	s_cselect_b32 s34, 1, 0
	s_and_b32 s34, s34, s24
	s_mul_i32 s35, s34, 0x1600
	s_sub_u32 s35, s29, s35
	s_lshr_b32 s36, s35, 7
	s_lshl_b32 s36, s36, 8
	s_lshl_b32 s37, s34, 7
	s_add_u32 s36, s36, s37
	s_and_b32 s37, s35, 0x7f
	s_add_u32 s36, s36, s37
	s_cmp_eq_u32 s24, 0
	s_cselect_b32 s36, s29, s36
	s_lshr_b32 s37, s36, 8
	s_mul_i32 s37, s37, s21
	s_add_u32 s37, s37, s27
	s_lshl_b32 s37, s37, 8
	s_and_b32 s38, s36, 0xff
	s_add_u32 s37, s37, s38
	s_lshl_b32 s37, s37, 7
	s_add_u32 s54, s22, s37
	s_addc_u32 s55, s23, 0
	s_mov_b32 s49, s13
	v_mad_u32_u24 v10, v2, s18, v1
	global_load_dwordx4 v[68:71], v3, s[72:73]
	global_load_dwordx4 v[72:75], v3, s[72:73] offset:16
	global_load_dwordx4 v[76:79], v10, s[56:57] nt
	global_load_dwordx4 v[80:83], v10, s[58:59] nt
	global_load_dwordx4 v[84:87], v10, s[60:61] nt
	global_load_dwordx4 v[88:91], v10, s[62:63] nt
	global_load_dwordx4 v[92:95], v10, s[64:65] nt
	global_load_dwordx4 v[96:99], v10, s[66:67] nt
	global_load_dwordx4 v[100:103], v10, s[68:69] nt
	global_load_dwordx4 v[104:107], v10, s[70:71] nt
	s_waitcnt vmcnt(10)
.Lp0_top:
	s_waitcnt vmcnt(14)
	s_cmp_eq_u32 s48, 0
	s_cbranch_scc1 .Lp0_nomul_pa
	v_mul_f32_e32 v36, v36, v28
	v_mul_f32_e32 v37, v37, v28
	v_mul_f32_e32 v38, v38, v28
	v_mul_f32_e32 v39, v39, v28
	v_mul_f32_e32 v40, v40, v29
	v_mul_f32_e32 v41, v41, v29
	v_mul_f32_e32 v42, v42, v29
	v_mul_f32_e32 v43, v43, v29
	v_mul_f32_e32 v44, v44, v30
	v_mul_f32_e32 v45, v45, v30
	v_mul_f32_e32 v46, v46, v30
	v_mul_f32_e32 v47, v47, v30
	v_mul_f32_e32 v48, v48, v31
	v_mul_f32_e32 v49, v49, v31
	v_mul_f32_e32 v50, v50, v31
	v_mul_f32_e32 v51, v51, v31
	v_mul_f32_e32 v52, v52, v32
	v_mul_f32_e32 v53, v53, v32
	v_mul_f32_e32 v54, v54, v32
	v_mul_f32_e32 v55, v55, v32
	v_mul_f32_e32 v56, v56, v33
	v_mul_f32_e32 v57, v57, v33
	v_mul_f32_e32 v58, v58, v33
	v_mul_f32_e32 v59, v59, v33
	v_mul_f32_e32 v60, v60, v34
	v_mul_f32_e32 v61, v61, v34
	v_mul_f32_e32 v62, v62, v34
	v_mul_f32_e32 v63, v63, v34
	v_mul_f32_e32 v64, v64, v35
	v_mul_f32_e32 v65, v65, v35
	v_mul_f32_e32 v66, v66, v35
	v_mul_f32_e32 v67, v67, v35
.Lp0_nomul_pa:
	v_cvt_pk_bf16_f32 v12, v36, v40
	v_cvt_pk_bf16_f32 v13, v44, v48
	v_cvt_pk_bf16_f32 v14, v52, v56
	v_cvt_pk_bf16_f32 v15, v60, v64
	v_cvt_pk_bf16_f32 v16, v37, v41
	v_cvt_pk_bf16_f32 v17, v45, v49
	v_cvt_pk_bf16_f32 v18, v53, v57
	v_cvt_pk_bf16_f32 v19, v61, v65
	v_cvt_pk_bf16_f32 v20, v38, v42
	v_cvt_pk_bf16_f32 v21, v46, v50
	v_cvt_pk_bf16_f32 v22, v54, v58
	v_cvt_pk_bf16_f32 v23, v62, v66
	v_cvt_pk_bf16_f32 v24, v39, v43
	v_cvt_pk_bf16_f32 v25, v47, v51
	v_cvt_pk_bf16_f32 v26, v55, v59
	v_cvt_pk_bf16_f32 v27, v63, v67
	s_mov_b32 s74, s46
	s_mov_b32 s75, s47
	s_add_i32 s25, s4, 2
	s_min_i32 s25, s25, s5
	s_lshl_b32 s25, s25, 11
	s_add_u32 s25, s25, s10

.Lp0_segok_l1:
	s_sub_u32 s26, s25, s7
	s_mul_hi_u32 s27, s26, s20
	s_mul_i32 s28, s27, s19
	s_sub_u32 s28, s26, s28
	s_lshl_b32 s29, s28, 5
	s_lshl_b32 s30, s27, 6
	s_mul_i32 s31, s30, s18
	s_lshl_b32 s34, s29, 2
	s_add_u32 s31, s31, s34
	s_add_u32 s56, s14, s31
	s_addc_u32 s57, s15, 0
	s_add_u32 s58, s56, s18
	s_addc_u32 s59, s57, 0
	s_add_u32 s60, s58, s18
	s_addc_u32 s61, s59, 0
	s_add_u32 s62, s60, s18
	s_addc_u32 s63, s61, 0
	s_add_u32 s64, s62, s18
	s_addc_u32 s65, s63, 0
	s_add_u32 s66, s64, s18
	s_addc_u32 s67, s65, 0
	s_add_u32 s68, s66, s18
	s_addc_u32 s69, s67, 0
	s_add_u32 s70, s68, s18
	s_addc_u32 s71, s69, 0
	s_lshl_b32 s34, s30, 2
	s_add_u32 s72, s16, s34
	s_addc_u32 s73, s17, 0
	s_cmpk_ge_u32 s29, 0x1600
	s_cselect_b32 s34, 1, 0
	s_and_b32 s34, s34, s24
	s_mul_i32 s35, s34, 0x1600
	s_sub_u32 s35, s29, s35
	s_lshr_b32 s36, s35, 7
	s_lshl_b32 s36, s36, 8
	s_lshl_b32 s37, s34, 7
	s_add_u32 s36, s36, s37
	s_and_b32 s37, s35, 0x7f
	s_add_u32 s36, s36, s37
	s_cmp_eq_u32 s24, 0
	s_cselect_b32 s36, s29, s36
	s_lshr_b32 s37, s36, 8
	s_mul_i32 s37, s37, s21
	s_add_u32 s37, s37, s27
	s_lshl_b32 s37, s37, 8
	s_and_b32 s38, s36, 0xff
	s_add_u32 s37, s37, s38
	s_lshl_b32 s37, s37, 7
	s_add_u32 s46, s22, s37
	s_addc_u32 s47, s23, 0
	s_mov_b32 s48, s13
	v_mad_u32_u24 v10, v2, s18, v1
	global_load_dwordx4 v[28:31], v3, s[72:73]
	global_load_dwordx4 v[32:35], v3, s[72:73] offset:16
	global_load_dwordx4 v[36:39], v10, s[56:57] nt
	global_load_dwordx4 v[40:43], v10, s[58:59] nt
	global_load_dwordx4 v[44:47], v10, s[60:61] nt
	global_load_dwordx4 v[48:51], v10, s[62:63] nt
	global_load_dwordx4 v[52:55], v10, s[64:65] nt
	global_load_dwordx4 v[56:59], v10, s[66:67] nt
	global_load_dwordx4 v[60:63], v10, s[68:69] nt
	global_load_dwordx4 v[64:67], v10, s[70:71] nt
	ds_write_b128 v4, v[12:15] offset:0
	ds_write_b128 v4, v[16:19] offset:128
	ds_write_b128 v4, v[20:23] offset:256
	ds_write_b128 v4, v[24:27] offset:384
	s_waitcnt lgkmcnt(0)
	ds_read_b128 v[12:15], v5 offset:0
	ds_read_b128 v[16:19], v6 offset:1024
	ds_read_b128 v[20:23], v7 offset:2048
	ds_read_b128 v[24:27], v8 offset:3072
	s_waitcnt lgkmcnt(0)
	global_store_dwordx4 v9, v[12:15], s[74:75] nt
	global_store_dwordx4 v9, v[16:19], s[74:75] offset:1024 nt
	global_store_dwordx4 v9, v[20:23], s[74:75] offset:2048 nt
	global_store_dwordx4 v9, v[24:27], s[74:75] offset:3072 nt
	s_waitcnt vmcnt(14)
	s_cmp_eq_u32 s49, 0
	s_cbranch_scc1 .Lp0_nomul_pb
	v_mul_f32_e32 v76, v76, v68
	v_mul_f32_e32 v77, v77, v68
	v_mul_f32_e32 v78, v78, v68
	v_mul_f32_e32 v79, v79, v68
	v_mul_f32_e32 v80, v80, v69
	v_mul_f32_e32 v81, v81, v69
	v_mul_f32_e32 v82, v82, v69
	v_mul_f32_e32 v83, v83, v69
	v_mul_f32_e32 v84, v84, v70
	v_mul_f32_e32 v85, v85, v70
	v_mul_f32_e32 v86, v86, v70
	v_mul_f32_e32 v87, v87, v70
	v_mul_f32_e32 v88, v88, v71
	v_mul_f32_e32 v89, v89, v71
	v_mul_f32_e32 v90, v90, v71
	v_mul_f32_e32 v91, v91, v71
	v_mul_f32_e32 v92, v92, v72
	v_mul_f32_e32 v93, v93, v72
	v_mul_f32_e32 v94, v94, v72
	v_mul_f32_e32 v95, v95, v72
	v_mul_f32_e32 v96, v96, v73
	v_mul_f32_e32 v97, v97, v73
	v_mul_f32_e32 v98, v98, v73
	v_mul_f32_e32 v99, v99, v73
	v_mul_f32_e32 v100, v100, v74
	v_mul_f32_e32 v101, v101, v74
	v_mul_f32_e32 v102, v102, v74
	v_mul_f32_e32 v103, v103, v74
	v_mul_f32_e32 v104, v104, v75
	v_mul_f32_e32 v105, v105, v75
	v_mul_f32_e32 v106, v106, v75
	v_mul_f32_e32 v107, v107, v75
.Lp0_nomul_pb:
	v_cvt_pk_bf16_f32 v12, v76, v80
	v_cvt_pk_bf16_f32 v13, v84, v88
	v_cvt_pk_bf16_f32 v14, v92, v96
	v_cvt_pk_bf16_f32 v15, v100, v104
	v_cvt_pk_bf16_f32 v16, v77, v81
	v_cvt_pk_bf16_f32 v17, v85, v89
	v_cvt_pk_bf16_f32 v18, v93, v97
	v_cvt_pk_bf16_f32 v19, v101, v105
	v_cvt_pk_bf16_f32 v20, v78, v82
	v_cvt_pk_bf16_f32 v21, v86, v90
	v_cvt_pk_bf16_f32 v22, v94, v98
	v_cvt_pk_bf16_f32 v23, v102, v106
	v_cvt_pk_bf16_f32 v24, v79, v83
	v_cvt_pk_bf16_f32 v25, v87, v91
	v_cvt_pk_bf16_f32 v26, v95, v99
	v_cvt_pk_bf16_f32 v27, v103, v107
	s_mov_b32 s74, s54
	s_mov_b32 s75, s55
	s_add_i32 s25, s4, 3
	s_min_i32 s25, s25, s5
	s_lshl_b32 s25, s25, 11
	s_add_u32 s25, s25, s10

.Lp0_segok_l2:
	s_sub_u32 s26, s25, s7
	s_mul_hi_u32 s27, s26, s20
	s_mul_i32 s28, s27, s19
	s_sub_u32 s28, s26, s28
	s_lshl_b32 s29, s28, 5
	s_lshl_b32 s30, s27, 6
	s_mul_i32 s31, s30, s18
	s_lshl_b32 s34, s29, 2
	s_add_u32 s31, s31, s34
	s_add_u32 s56, s14, s31
	s_addc_u32 s57, s15, 0
	s_add_u32 s58, s56, s18
	s_addc_u32 s59, s57, 0
	s_add_u32 s60, s58, s18
	s_addc_u32 s61, s59, 0
	s_add_u32 s62, s60, s18
	s_addc_u32 s63, s61, 0
	s_add_u32 s64, s62, s18
	s_addc_u32 s65, s63, 0
	s_add_u32 s66, s64, s18
	s_addc_u32 s67, s65, 0
	s_add_u32 s68, s66, s18
	s_addc_u32 s69, s67, 0
	s_add_u32 s70, s68, s18
	s_addc_u32 s71, s69, 0
	s_lshl_b32 s34, s30, 2
	s_add_u32 s72, s16, s34
	s_addc_u32 s73, s17, 0
	s_cmpk_ge_u32 s29, 0x1600
	s_cselect_b32 s34, 1, 0
	s_and_b32 s34, s34, s24
	s_mul_i32 s35, s34, 0x1600
	s_sub_u32 s35, s29, s35
	s_lshr_b32 s36, s35, 7
	s_lshl_b32 s36, s36, 8
	s_lshl_b32 s37, s34, 7
	s_add_u32 s36, s36, s37
	s_and_b32 s37, s35, 0x7f
	s_add_u32 s36, s36, s37
	s_cmp_eq_u32 s24, 0
	s_cselect_b32 s36, s29, s36
	s_lshr_b32 s37, s36, 8
	s_mul_i32 s37, s37, s21
	s_add_u32 s37, s37, s27
	s_lshl_b32 s37, s37, 8
	s_and_b32 s38, s36, 0xff
	s_add_u32 s37, s37, s38
	s_lshl_b32 s37, s37, 7
	s_add_u32 s54, s22, s37
	s_addc_u32 s55, s23, 0
	s_mov_b32 s49, s13
	v_mad_u32_u24 v10, v2, s18, v1
	global_load_dwordx4 v[68:71], v3, s[72:73]
	global_load_dwordx4 v[72:75], v3, s[72:73] offset:16
	global_load_dwordx4 v[76:79], v10, s[56:57] nt
	global_load_dwordx4 v[80:83], v10, s[58:59] nt
	global_load_dwordx4 v[84:87], v10, s[60:61] nt
	global_load_dwordx4 v[88:91], v10, s[62:63] nt
	global_load_dwordx4 v[92:95], v10, s[64:65] nt
	global_load_dwordx4 v[96:99], v10, s[66:67] nt
	global_load_dwordx4 v[100:103], v10, s[68:69] nt
	global_load_dwordx4 v[104:107], v10, s[70:71] nt
	ds_write_b128 v4, v[12:15] offset:0
	ds_write_b128 v4, v[16:19] offset:128
	ds_write_b128 v4, v[20:23] offset:256
	ds_write_b128 v4, v[24:27] offset:384
	s_waitcnt lgkmcnt(0)
	ds_read_b128 v[12:15], v5 offset:0
	ds_read_b128 v[16:19], v6 offset:1024
	ds_read_b128 v[20:23], v7 offset:2048
	ds_read_b128 v[24:27], v8 offset:3072
	s_waitcnt lgkmcnt(0)
	global_store_dwordx4 v9, v[12:15], s[74:75] nt
	global_store_dwordx4 v9, v[16:19], s[74:75] offset:1024 nt
	global_store_dwordx4 v9, v[20:23], s[74:75] offset:2048 nt
	global_store_dwordx4 v9, v[24:27], s[74:75] offset:3072 nt
	s_add_i32 s4, s4, 2
	s_cmpk_lt_i32 s4, 0x50
	s_cbranch_scc1 .Lp0_top
	s_waitcnt vmcnt(0)
